# v014 + P1 gate-tile epilogue: -log2e folded into the 8 per-row rstd broadcast registers, 128 per-element v_mul removed (f32, same kinds)
# speedup vs baseline: 1.0005x; 1.0005x over previous
.LBB0_250:
	s_waitcnt vmcnt(0)
	v_mul_f32_e32 v156, 0xbfb8aa3b, v156
	v_mul_f32_e32 v160, 0xbfb8aa3b, v160
	v_mul_f32_e32 v164, 0xbfb8aa3b, v164
	v_mul_f32_e32 v168, 0xbfb8aa3b, v168
	v_mul_f32_e32 v172, 0xbfb8aa3b, v172
	v_mul_f32_e32 v176, 0xbfb8aa3b, v176
	v_mul_f32_e32 v180, 0xbfb8aa3b, v180
	v_mul_f32_e32 v184, 0xbfb8aa3b, v184
	v_pk_mul_f32 v[132:133], v[128:129], v[184:185] op_sel_hi:[1,0]
	v_pk_mul_f32 v[134:135], v[126:127], v[184:185] op_sel_hi:[1,0]
	v_exp_f32_e32 v132, v132
	v_exp_f32_e32 v133, v133
	v_exp_f32_e32 v157, v134
	v_exp_f32_e32 v159, v135
	v_pk_mul_f32 v[134:135], v[122:123], v[184:185] op_sel_hi:[1,0]
	v_add_f32_e32 v132, 1.0, v132
	v_rcp_f32_e32 v161, v132
	v_add_f32_e32 v132, 1.0, v133
	v_exp_f32_e32 v133, v134
	v_lshl_add_u32 v130, s54, 8, v185
	s_waitcnt lgkmcnt(0)
	v_mov_b32_e32 v131, v147
	v_exp_f32_e32 v134, v135
	v_lshl_add_u64 v[130:131], v[130:131], 1, s[64:65]
	v_mad_i64_i32 v[136:137], s[0:1], v186, s97, v[130:131]
	v_pk_mul_f32 v[186:187], v[124:125], v[184:185] op_sel_hi:[1,0]
	v_rcp_f32_e32 v135, v132
	v_add_f32_e32 v132, 1.0, v133
	v_rcp_f32_e32 v163, v132
	v_add_f32_e32 v132, 1.0, v134
	v_exp_f32_e32 v133, v186
	v_exp_f32_e32 v134, v187
	v_rcp_f32_e32 v165, v132
	v_add_f32_e32 v132, 1.0, v133
	v_add_f32_e32 v157, 1.0, v157
	v_add_f32_e32 v159, 1.0, v159
	v_rcp_f32_e32 v167, v132
	v_add_f32_e32 v132, 1.0, v134
	v_rcp_f32_e32 v157, v157
	v_rcp_f32_e32 v159, v159
	v_rcp_f32_e32 v169, v132
	v_cvt_pk_bf16_f32 v133, v161, v135
	v_cvt_pk_bf16_f32 v134, v163, v165
	v_cvt_pk_bf16_f32 v132, v157, v159
	v_cvt_pk_bf16_f32 v135, v167, v169
	global_store_dwordx4 v[136:137], v[132:135], off
	v_pk_mul_f32 v[186:187], v[116:117], v[184:185] op_sel_hi:[1,0]
	s_nop 0
	v_pk_mul_f32 v[132:133], v[120:121], v[184:185] op_sel_hi:[1,0]
	v_pk_mul_f32 v[134:135], v[118:119], v[184:185] op_sel_hi:[1,0]
	v_exp_f32_e32 v132, v132
	v_exp_f32_e32 v133, v133
	v_exp_f32_e32 v157, v134
	v_exp_f32_e32 v159, v135
	v_pk_mul_f32 v[134:135], v[114:115], v[184:185] op_sel_hi:[1,0]
	v_add_f32_e32 v132, 1.0, v132
	v_rcp_f32_e32 v161, v132
	v_add_f32_e32 v132, 1.0, v133
	v_exp_f32_e32 v133, v134
	v_exp_f32_e32 v134, v135
	v_rcp_f32_e32 v135, v132
	v_add_f32_e32 v132, 1.0, v133
	v_rcp_f32_e32 v163, v132
	v_add_f32_e32 v132, 1.0, v134
	v_exp_f32_e32 v133, v186
	v_exp_f32_e32 v134, v187
	v_rcp_f32_e32 v165, v132
	v_add_f32_e32 v132, 1.0, v133
	v_add_f32_e32 v157, 1.0, v157
	v_add_f32_e32 v159, 1.0, v159
	v_rcp_f32_e32 v167, v132
	v_add_f32_e32 v132, 1.0, v134
	v_rcp_f32_e32 v157, v157
	v_rcp_f32_e32 v159, v159
	v_rcp_f32_e32 v169, v132
	v_cvt_pk_bf16_f32 v133, v161, v135
	v_cvt_pk_bf16_f32 v134, v163, v165
	v_cvt_pk_bf16_f32 v132, v157, v159
	v_cvt_pk_bf16_f32 v135, v167, v169
	global_store_dwordx4 v[136:137], v[132:135], off offset:256
	v_mad_i64_i32 v[136:137], s[0:1], v182, s97, v[130:131]
	s_nop 0
	v_pk_mul_f32 v[132:133], v[112:113], v[180:181] op_sel_hi:[1,0]
	v_pk_mul_f32 v[134:135], v[110:111], v[180:181] op_sel_hi:[1,0]
	v_exp_f32_e32 v132, v132
	v_exp_f32_e32 v133, v133
	v_exp_f32_e32 v157, v134
	v_exp_f32_e32 v159, v135
	v_pk_mul_f32 v[134:135], v[106:107], v[180:181] op_sel_hi:[1,0]
	v_add_f32_e32 v132, 1.0, v132
	v_rcp_f32_e32 v161, v132
	v_add_f32_e32 v132, 1.0, v133
	v_exp_f32_e32 v133, v134
	v_exp_f32_e32 v134, v135
	v_pk_mul_f32 v[182:183], v[108:109], v[180:181] op_sel_hi:[1,0]
	v_rcp_f32_e32 v135, v132
	v_add_f32_e32 v132, 1.0, v133
	v_rcp_f32_e32 v163, v132
	v_add_f32_e32 v132, 1.0, v134
	v_exp_f32_e32 v133, v182
	v_exp_f32_e32 v134, v183
	v_rcp_f32_e32 v165, v132
	v_add_f32_e32 v132, 1.0, v133
	v_add_f32_e32 v157, 1.0, v157
	v_add_f32_e32 v159, 1.0, v159
	v_rcp_f32_e32 v167, v132
	v_add_f32_e32 v132, 1.0, v134
	v_rcp_f32_e32 v157, v157
	v_rcp_f32_e32 v159, v159
	v_rcp_f32_e32 v169, v132
	v_cvt_pk_bf16_f32 v133, v161, v135
	v_cvt_pk_bf16_f32 v134, v163, v165
	v_cvt_pk_bf16_f32 v132, v157, v159
	v_cvt_pk_bf16_f32 v135, v167, v169
	global_store_dwordx4 v[136:137], v[132:135], off
	v_pk_mul_f32 v[182:183], v[100:101], v[180:181] op_sel_hi:[1,0]
	s_nop 0
	v_pk_mul_f32 v[132:133], v[104:105], v[180:181] op_sel_hi:[1,0]
	v_pk_mul_f32 v[134:135], v[102:103], v[180:181] op_sel_hi:[1,0]
	v_exp_f32_e32 v132, v132
	v_exp_f32_e32 v133, v133
	v_exp_f32_e32 v157, v134
	v_exp_f32_e32 v159, v135
	v_pk_mul_f32 v[134:135], v[98:99], v[180:181] op_sel_hi:[1,0]
	v_add_f32_e32 v132, 1.0, v132
	v_rcp_f32_e32 v161, v132
	v_add_f32_e32 v132, 1.0, v133
	v_exp_f32_e32 v133, v134
	v_exp_f32_e32 v134, v135
	v_rcp_f32_e32 v135, v132
	v_add_f32_e32 v132, 1.0, v133
	v_rcp_f32_e32 v163, v132
	v_add_f32_e32 v132, 1.0, v134
	v_exp_f32_e32 v133, v182
	v_exp_f32_e32 v134, v183
	v_rcp_f32_e32 v165, v132
	v_add_f32_e32 v132, 1.0, v133
	v_add_f32_e32 v157, 1.0, v157
	v_add_f32_e32 v159, 1.0, v159
	v_rcp_f32_e32 v167, v132
	v_add_f32_e32 v132, 1.0, v134
	v_rcp_f32_e32 v157, v157
	v_rcp_f32_e32 v159, v159
	v_rcp_f32_e32 v169, v132
	v_cvt_pk_bf16_f32 v133, v161, v135
	v_cvt_pk_bf16_f32 v134, v163, v165
	v_cvt_pk_bf16_f32 v132, v157, v159
	v_cvt_pk_bf16_f32 v135, v167, v169
	global_store_dwordx4 v[136:137], v[132:135], off offset:256
	v_mad_i64_i32 v[136:137], s[0:1], v178, s97, v[130:131]
	s_nop 0
	v_pk_mul_f32 v[132:133], v[96:97], v[176:177] op_sel_hi:[1,0]
	v_pk_mul_f32 v[134:135], v[94:95], v[176:177] op_sel_hi:[1,0]
	v_exp_f32_e32 v132, v132
	v_exp_f32_e32 v133, v133
	v_exp_f32_e32 v157, v134
	v_exp_f32_e32 v159, v135
	v_pk_mul_f32 v[134:135], v[90:91], v[176:177] op_sel_hi:[1,0]
	v_add_f32_e32 v132, 1.0, v132
	v_rcp_f32_e32 v161, v132
	v_add_f32_e32 v132, 1.0, v133
	v_exp_f32_e32 v133, v134
	v_exp_f32_e32 v134, v135
	v_pk_mul_f32 v[178:179], v[92:93], v[176:177] op_sel_hi:[1,0]
	v_rcp_f32_e32 v135, v132
	v_add_f32_e32 v132, 1.0, v133
	v_rcp_f32_e32 v163, v132
	v_add_f32_e32 v132, 1.0, v134
	v_exp_f32_e32 v133, v178
	v_exp_f32_e32 v134, v179
	v_rcp_f32_e32 v165, v132
	v_add_f32_e32 v132, 1.0, v133
	v_add_f32_e32 v157, 1.0, v157
	v_add_f32_e32 v159, 1.0, v159
	v_rcp_f32_e32 v167, v132
	v_add_f32_e32 v132, 1.0, v134
	v_rcp_f32_e32 v157, v157
	v_rcp_f32_e32 v159, v159
	v_rcp_f32_e32 v169, v132
	v_cvt_pk_bf16_f32 v133, v161, v135
	v_cvt_pk_bf16_f32 v134, v163, v165
	v_cvt_pk_bf16_f32 v132, v157, v159
	v_cvt_pk_bf16_f32 v135, v167, v169
	global_store_dwordx4 v[136:137], v[132:135], off
	v_pk_mul_f32 v[178:179], v[84:85], v[176:177] op_sel_hi:[1,0]
	s_nop 0
	v_pk_mul_f32 v[132:133], v[88:89], v[176:177] op_sel_hi:[1,0]
	v_pk_mul_f32 v[134:135], v[86:87], v[176:177] op_sel_hi:[1,0]
	v_exp_f32_e32 v132, v132
	v_exp_f32_e32 v133, v133
	v_exp_f32_e32 v157, v134
	v_exp_f32_e32 v159, v135
	v_pk_mul_f32 v[134:135], v[82:83], v[176:177] op_sel_hi:[1,0]
	v_add_f32_e32 v132, 1.0, v132
	v_rcp_f32_e32 v161, v132
	v_add_f32_e32 v132, 1.0, v133
	v_exp_f32_e32 v133, v134
	v_exp_f32_e32 v134, v135
	v_rcp_f32_e32 v135, v132
	v_add_f32_e32 v132, 1.0, v133
	v_rcp_f32_e32 v163, v132
	v_add_f32_e32 v132, 1.0, v134
	v_exp_f32_e32 v133, v178
	v_exp_f32_e32 v134, v179
	v_rcp_f32_e32 v165, v132
	v_add_f32_e32 v132, 1.0, v133
	v_add_f32_e32 v157, 1.0, v157
	v_add_f32_e32 v159, 1.0, v159
	v_rcp_f32_e32 v167, v132
	v_add_f32_e32 v132, 1.0, v134
	v_rcp_f32_e32 v157, v157
	v_rcp_f32_e32 v159, v159
	v_rcp_f32_e32 v169, v132
	v_cvt_pk_bf16_f32 v133, v161, v135
	v_cvt_pk_bf16_f32 v134, v163, v165
	v_cvt_pk_bf16_f32 v132, v157, v159
	v_cvt_pk_bf16_f32 v135, v167, v169
	global_store_dwordx4 v[136:137], v[132:135], off offset:256
	v_mad_i64_i32 v[136:137], s[0:1], v174, s97, v[130:131]
	s_nop 0
	v_pk_mul_f32 v[132:133], v[80:81], v[172:173] op_sel_hi:[1,0]
	v_pk_mul_f32 v[134:135], v[78:79], v[172:173] op_sel_hi:[1,0]
	v_exp_f32_e32 v132, v132
	v_exp_f32_e32 v133, v133
	v_exp_f32_e32 v157, v134
	v_exp_f32_e32 v159, v135
	v_pk_mul_f32 v[134:135], v[74:75], v[172:173] op_sel_hi:[1,0]
	v_add_f32_e32 v132, 1.0, v132
	v_rcp_f32_e32 v161, v132
	v_add_f32_e32 v132, 1.0, v133
	v_exp_f32_e32 v133, v134
	v_exp_f32_e32 v134, v135
	v_pk_mul_f32 v[174:175], v[76:77], v[172:173] op_sel_hi:[1,0]
	v_rcp_f32_e32 v135, v132
	v_add_f32_e32 v132, 1.0, v133
	v_rcp_f32_e32 v163, v132
	v_add_f32_e32 v132, 1.0, v134
	v_exp_f32_e32 v133, v174
	v_exp_f32_e32 v134, v175
	v_rcp_f32_e32 v165, v132
	v_add_f32_e32 v132, 1.0, v133
	v_add_f32_e32 v157, 1.0, v157
	v_add_f32_e32 v159, 1.0, v159
	v_rcp_f32_e32 v167, v132
	v_add_f32_e32 v132, 1.0, v134
	v_rcp_f32_e32 v157, v157
	v_rcp_f32_e32 v159, v159
	v_rcp_f32_e32 v169, v132
	v_cvt_pk_bf16_f32 v133, v161, v135
	v_cvt_pk_bf16_f32 v134, v163, v165
	v_cvt_pk_bf16_f32 v132, v157, v159
	v_cvt_pk_bf16_f32 v135, v167, v169
	global_store_dwordx4 v[136:137], v[132:135], off
	v_pk_mul_f32 v[174:175], v[68:69], v[172:173] op_sel_hi:[1,0]
	s_nop 0
	v_pk_mul_f32 v[132:133], v[72:73], v[172:173] op_sel_hi:[1,0]
	v_pk_mul_f32 v[134:135], v[70:71], v[172:173] op_sel_hi:[1,0]
	v_exp_f32_e32 v132, v132
	v_exp_f32_e32 v133, v133
	v_exp_f32_e32 v157, v134
	v_exp_f32_e32 v159, v135
	v_pk_mul_f32 v[134:135], v[66:67], v[172:173] op_sel_hi:[1,0]
	v_add_f32_e32 v132, 1.0, v132
	v_rcp_f32_e32 v161, v132
	v_add_f32_e32 v132, 1.0, v133
	v_exp_f32_e32 v133, v134
	v_exp_f32_e32 v134, v135
	v_rcp_f32_e32 v135, v132
	v_add_f32_e32 v132, 1.0, v133
	v_rcp_f32_e32 v163, v132
	v_add_f32_e32 v132, 1.0, v134
	v_exp_f32_e32 v133, v174
	v_exp_f32_e32 v134, v175
	v_rcp_f32_e32 v165, v132
	v_add_f32_e32 v132, 1.0, v133
	v_add_f32_e32 v157, 1.0, v157
	v_add_f32_e32 v159, 1.0, v159
	v_rcp_f32_e32 v167, v132
	v_add_f32_e32 v132, 1.0, v134
	v_rcp_f32_e32 v157, v157
	v_rcp_f32_e32 v159, v159
	v_rcp_f32_e32 v169, v132
	v_cvt_pk_bf16_f32 v133, v161, v135
	v_cvt_pk_bf16_f32 v134, v163, v165
	v_cvt_pk_bf16_f32 v132, v157, v159
	v_cvt_pk_bf16_f32 v135, v167, v169
	global_store_dwordx4 v[136:137], v[132:135], off offset:256
	v_mad_i64_i32 v[136:137], s[0:1], v170, s97, v[130:131]
	s_nop 0
	v_pk_mul_f32 v[132:133], v[64:65], v[168:169] op_sel_hi:[1,0]
	v_pk_mul_f32 v[134:135], v[62:63], v[168:169] op_sel_hi:[1,0]
	v_exp_f32_e32 v132, v132
	v_exp_f32_e32 v133, v133
	v_exp_f32_e32 v157, v134
	v_exp_f32_e32 v159, v135
	v_pk_mul_f32 v[134:135], v[58:59], v[168:169] op_sel_hi:[1,0]
	v_add_f32_e32 v132, 1.0, v132
	v_rcp_f32_e32 v161, v132
	v_add_f32_e32 v132, 1.0, v133
	v_exp_f32_e32 v133, v134
	v_exp_f32_e32 v134, v135
	v_pk_mul_f32 v[170:171], v[60:61], v[168:169] op_sel_hi:[1,0]
	v_rcp_f32_e32 v135, v132
	v_add_f32_e32 v132, 1.0, v133
	v_rcp_f32_e32 v163, v132
	v_add_f32_e32 v132, 1.0, v134
	v_exp_f32_e32 v133, v170
	v_exp_f32_e32 v134, v171
	v_rcp_f32_e32 v165, v132
	v_add_f32_e32 v132, 1.0, v133
	v_add_f32_e32 v157, 1.0, v157
	v_add_f32_e32 v159, 1.0, v159
	v_rcp_f32_e32 v167, v132
	v_add_f32_e32 v132, 1.0, v134
	v_rcp_f32_e32 v157, v157
	v_rcp_f32_e32 v159, v159
	v_rcp_f32_e32 v169, v132
	v_cvt_pk_bf16_f32 v133, v161, v135
	v_cvt_pk_bf16_f32 v134, v163, v165
	v_cvt_pk_bf16_f32 v132, v157, v159
	v_cvt_pk_bf16_f32 v135, v167, v169
	global_store_dwordx4 v[136:137], v[132:135], off
	v_pk_mul_f32 v[170:171], v[52:53], v[168:169] op_sel_hi:[1,0]
	s_nop 0
	v_pk_mul_f32 v[132:133], v[56:57], v[168:169] op_sel_hi:[1,0]
	v_pk_mul_f32 v[134:135], v[54:55], v[168:169] op_sel_hi:[1,0]
	v_exp_f32_e32 v132, v132
	v_exp_f32_e32 v133, v133
	v_exp_f32_e32 v157, v134
	v_exp_f32_e32 v159, v135
	v_pk_mul_f32 v[134:135], v[50:51], v[168:169] op_sel_hi:[1,0]
	v_add_f32_e32 v132, 1.0, v132
	v_rcp_f32_e32 v161, v132
	v_add_f32_e32 v132, 1.0, v133
	v_exp_f32_e32 v133, v134
	v_exp_f32_e32 v134, v135
	v_rcp_f32_e32 v135, v132
	v_add_f32_e32 v132, 1.0, v133
	v_rcp_f32_e32 v163, v132
	v_add_f32_e32 v132, 1.0, v134
	v_exp_f32_e32 v133, v170
	v_exp_f32_e32 v134, v171
	v_rcp_f32_e32 v165, v132
	v_add_f32_e32 v132, 1.0, v133
	v_add_f32_e32 v157, 1.0, v157
	v_add_f32_e32 v159, 1.0, v159
	v_rcp_f32_e32 v167, v132
	v_add_f32_e32 v132, 1.0, v134
	v_rcp_f32_e32 v157, v157
	v_rcp_f32_e32 v159, v159
	v_rcp_f32_e32 v168, v132
	v_cvt_pk_bf16_f32 v133, v161, v135
	v_cvt_pk_bf16_f32 v134, v163, v165
	v_cvt_pk_bf16_f32 v132, v157, v159
	v_cvt_pk_bf16_f32 v135, v167, v168
	global_store_dwordx4 v[136:137], v[132:135], off offset:256
	v_mad_i64_i32 v[136:137], s[0:1], v166, s97, v[130:131]
	s_nop 0
	v_pk_mul_f32 v[132:133], v[48:49], v[164:165] op_sel_hi:[1,0]
	v_pk_mul_f32 v[134:135], v[46:47], v[164:165] op_sel_hi:[1,0]
	v_exp_f32_e32 v132, v132
	v_exp_f32_e32 v133, v133
	v_exp_f32_e32 v157, v134
	v_exp_f32_e32 v159, v135
	v_pk_mul_f32 v[134:135], v[42:43], v[164:165] op_sel_hi:[1,0]
	v_add_f32_e32 v132, 1.0, v132
	v_rcp_f32_e32 v161, v132
	v_add_f32_e32 v132, 1.0, v133
	v_exp_f32_e32 v133, v134
	v_exp_f32_e32 v134, v135
	v_pk_mul_f32 v[166:167], v[44:45], v[164:165] op_sel_hi:[1,0]
	v_rcp_f32_e32 v135, v132
	v_add_f32_e32 v132, 1.0, v133
	v_rcp_f32_e32 v163, v132
	v_add_f32_e32 v132, 1.0, v134
	v_exp_f32_e32 v133, v166
	v_exp_f32_e32 v134, v167
	v_rcp_f32_e32 v165, v132
	v_add_f32_e32 v132, 1.0, v133
	v_add_f32_e32 v157, 1.0, v157
	v_add_f32_e32 v159, 1.0, v159
	v_rcp_f32_e32 v166, v132
	v_add_f32_e32 v132, 1.0, v134
	v_rcp_f32_e32 v157, v157
	v_rcp_f32_e32 v159, v159
	v_rcp_f32_e32 v167, v132
	v_cvt_pk_bf16_f32 v133, v161, v135
	v_cvt_pk_bf16_f32 v134, v163, v165
	v_cvt_pk_bf16_f32 v132, v157, v159
	v_cvt_pk_bf16_f32 v135, v166, v167
	global_store_dwordx4 v[136:137], v[132:135], off
	v_pk_mul_f32 v[166:167], v[36:37], v[164:165] op_sel_hi:[1,0]
	s_nop 0
	v_pk_mul_f32 v[132:133], v[40:41], v[164:165] op_sel_hi:[1,0]
	v_pk_mul_f32 v[134:135], v[38:39], v[164:165] op_sel_hi:[1,0]
	v_exp_f32_e32 v132, v132
	v_exp_f32_e32 v133, v133
	v_exp_f32_e32 v157, v134
	v_exp_f32_e32 v159, v135
	v_pk_mul_f32 v[134:135], v[34:35], v[164:165] op_sel_hi:[1,0]
	v_add_f32_e32 v132, 1.0, v132
	v_rcp_f32_e32 v161, v132
	v_add_f32_e32 v132, 1.0, v133
	v_exp_f32_e32 v133, v134
	v_exp_f32_e32 v134, v135
	v_rcp_f32_e32 v135, v132
	v_add_f32_e32 v132, 1.0, v133
	v_rcp_f32_e32 v163, v132
	v_add_f32_e32 v132, 1.0, v134
	v_exp_f32_e32 v133, v166
	v_exp_f32_e32 v134, v167
	v_rcp_f32_e32 v164, v132
	v_add_f32_e32 v132, 1.0, v133
	v_add_f32_e32 v157, 1.0, v157
	v_add_f32_e32 v159, 1.0, v159
	v_rcp_f32_e32 v165, v132
	v_add_f32_e32 v132, 1.0, v134
	v_rcp_f32_e32 v157, v157
	v_rcp_f32_e32 v159, v159
	v_rcp_f32_e32 v166, v132
	v_cvt_pk_bf16_f32 v133, v161, v135
	v_cvt_pk_bf16_f32 v134, v163, v164
	v_cvt_pk_bf16_f32 v132, v157, v159
	v_cvt_pk_bf16_f32 v135, v165, v166
	global_store_dwordx4 v[136:137], v[132:135], off offset:256
	v_mad_i64_i32 v[136:137], s[0:1], v162, s97, v[130:131]
	s_nop 0
	v_pk_mul_f32 v[132:133], v[32:33], v[160:161] op_sel_hi:[1,0]
	v_pk_mul_f32 v[134:135], v[30:31], v[160:161] op_sel_hi:[1,0]
	v_exp_f32_e32 v132, v132
	v_exp_f32_e32 v133, v133
	v_exp_f32_e32 v157, v134
	v_exp_f32_e32 v159, v135
	v_pk_mul_f32 v[134:135], v[26:27], v[160:161] op_sel_hi:[1,0]
	v_add_f32_e32 v132, 1.0, v132
	v_pk_mul_f32 v[162:163], v[28:29], v[160:161] op_sel_hi:[1,0]
	v_rcp_f32_e32 v161, v132
	v_add_f32_e32 v132, 1.0, v133
	v_exp_f32_e32 v133, v134
	v_exp_f32_e32 v134, v135
	v_rcp_f32_e32 v135, v132
	v_add_f32_e32 v132, 1.0, v133
	v_rcp_f32_e32 v164, v132
	v_add_f32_e32 v132, 1.0, v134
	v_exp_f32_e32 v133, v162
	v_exp_f32_e32 v134, v163
	v_rcp_f32_e32 v162, v132
	v_add_f32_e32 v132, 1.0, v133
	v_add_f32_e32 v157, 1.0, v157
	v_add_f32_e32 v159, 1.0, v159
	v_rcp_f32_e32 v163, v132
	v_add_f32_e32 v132, 1.0, v134
	v_rcp_f32_e32 v157, v157
	v_rcp_f32_e32 v159, v159
	v_rcp_f32_e32 v165, v132
	v_cvt_pk_bf16_f32 v133, v161, v135
	v_cvt_pk_bf16_f32 v134, v164, v162
	v_cvt_pk_bf16_f32 v132, v157, v159
	v_cvt_pk_bf16_f32 v135, v163, v165
	global_store_dwordx4 v[136:137], v[132:135], off
	v_pk_mul_f32 v[162:163], v[20:21], v[160:161] op_sel_hi:[1,0]
	s_nop 0
	v_pk_mul_f32 v[132:133], v[24:25], v[160:161] op_sel_hi:[1,0]
	v_pk_mul_f32 v[134:135], v[22:23], v[160:161] op_sel_hi:[1,0]
	v_exp_f32_e32 v132, v132
	v_exp_f32_e32 v133, v133
	v_exp_f32_e32 v157, v134
	v_exp_f32_e32 v159, v135
	v_pk_mul_f32 v[134:135], v[18:19], v[160:161] op_sel_hi:[1,0]
	v_add_f32_e32 v132, 1.0, v132
	v_rcp_f32_e32 v160, v132
	v_add_f32_e32 v132, 1.0, v133
	v_exp_f32_e32 v133, v134
	v_exp_f32_e32 v134, v135
	v_rcp_f32_e32 v135, v132
	v_add_f32_e32 v132, 1.0, v133
	v_rcp_f32_e32 v161, v132
	v_add_f32_e32 v132, 1.0, v134
	v_exp_f32_e32 v133, v162
	v_exp_f32_e32 v134, v163
	v_rcp_f32_e32 v162, v132
	v_add_f32_e32 v132, 1.0, v133
	v_add_f32_e32 v157, 1.0, v157
	v_add_f32_e32 v159, 1.0, v159
	v_rcp_f32_e32 v163, v132
	v_add_f32_e32 v132, 1.0, v134
	v_rcp_f32_e32 v157, v157
	v_rcp_f32_e32 v159, v159
	v_rcp_f32_e32 v164, v132
	v_cvt_pk_bf16_f32 v133, v160, v135
	v_cvt_pk_bf16_f32 v134, v161, v162
	v_cvt_pk_bf16_f32 v132, v157, v159
	v_cvt_pk_bf16_f32 v135, v163, v164
	global_store_dwordx4 v[136:137], v[132:135], off offset:256
	v_pk_mul_f32 v[136:137], v[12:13], v[156:157] op_sel_hi:[1,0]
	s_nop 0
	v_mad_i64_i32 v[134:135], s[0:1], v158, s97, v[130:131]
	v_pk_mul_f32 v[130:131], v[16:17], v[156:157] op_sel_hi:[1,0]
	v_pk_mul_f32 v[132:133], v[14:15], v[156:157] op_sel_hi:[1,0]
	v_exp_f32_e32 v157, v132
	v_exp_f32_e32 v130, v130
	v_exp_f32_e32 v131, v131
	v_exp_f32_e32 v158, v133
	v_pk_mul_f32 v[132:133], v[10:11], v[156:157] op_sel_hi:[1,0]
	v_add_f32_e32 v130, 1.0, v130
	v_rcp_f32_e32 v159, v130
	v_add_f32_e32 v130, 1.0, v131
	v_exp_f32_e32 v131, v132
	v_exp_f32_e32 v132, v133
	v_rcp_f32_e32 v133, v130
	v_add_f32_e32 v130, 1.0, v131
	v_rcp_f32_e32 v160, v130
	v_add_f32_e32 v130, 1.0, v132
	v_exp_f32_e32 v131, v136
	v_exp_f32_e32 v132, v137
	v_rcp_f32_e32 v136, v130
	v_add_f32_e32 v130, 1.0, v131
	v_add_f32_e32 v157, 1.0, v157
	v_add_f32_e32 v158, 1.0, v158
	v_rcp_f32_e32 v137, v130
	v_add_f32_e32 v130, 1.0, v132
	v_rcp_f32_e32 v157, v157
	v_rcp_f32_e32 v158, v158
	v_rcp_f32_e32 v161, v130
	v_cvt_pk_bf16_f32 v131, v159, v133
	v_cvt_pk_bf16_f32 v132, v160, v136
	v_cvt_pk_bf16_f32 v130, v157, v158
	v_cvt_pk_bf16_f32 v133, v137, v161
	global_store_dwordx4 v[134:135], v[130:133], off
	v_pk_mul_f32 v[136:137], v[4:5], v[156:157] op_sel_hi:[1,0]
	s_nop 0
	v_pk_mul_f32 v[130:131], v[8:9], v[156:157] op_sel_hi:[1,0]
	v_pk_mul_f32 v[132:133], v[6:7], v[156:157] op_sel_hi:[1,0]
	v_exp_f32_e32 v157, v132
	v_exp_f32_e32 v130, v130
	v_exp_f32_e32 v158, v133
	v_exp_f32_e32 v131, v131
	v_pk_mul_f32 v[132:133], v[2:3], v[156:157] op_sel_hi:[1,0]
	v_add_f32_e32 v130, 1.0, v130
	v_add_f32_e32 v156, 1.0, v157
	v_add_f32_e32 v157, 1.0, v158
	v_rcp_f32_e32 v158, v130
	v_add_f32_e32 v130, 1.0, v131
	v_exp_f32_e32 v131, v132
	v_exp_f32_e32 v132, v133
	v_rcp_f32_e32 v133, v130
	v_add_f32_e32 v130, 1.0, v131
	v_rcp_f32_e32 v159, v130
	v_add_f32_e32 v130, 1.0, v132
	v_exp_f32_e32 v131, v136
	v_exp_f32_e32 v132, v137
	v_rcp_f32_e32 v136, v130
	v_add_f32_e32 v130, 1.0, v131
	v_rcp_f32_e32 v137, v130
	v_add_f32_e32 v130, 1.0, v132
	v_rcp_f32_e32 v156, v156
	v_rcp_f32_e32 v157, v157
	v_rcp_f32_e32 v160, v130
	v_cvt_pk_bf16_f32 v131, v158, v133
	v_cvt_pk_bf16_f32 v132, v159, v136
	v_cvt_pk_bf16_f32 v130, v156, v157
	v_cvt_pk_bf16_f32 v133, v137, v160
	global_store_dwordx4 v[134:135], v[130:133], off offset:256
